# v53: v45 + attention units (.LBB0_415): running max of row group 1 carried as the QK MFMA C operand (tuple v[236:251] = -m), no v_sub before v_exp on the no-rescale path
# speedup vs baseline: 1.0129x; 1.0057x over previous
; #define LAS __attribute__((address_space(3)))
; __device__ __forceinline__ int opaque_tid() { int t = threadIdx.x; asm volatile("" : "+v"(t)); return t; }
; #define AT_LOAD(t_) do { const bf16_t* kn = ksrc + (size_t)(t_) * AKT * INW; const bf16_t* vn = vsrc + (t_) * AKT; \
;         kreg0 = *(const u32x4*)kn; kreg1 = *(const u32x4*)(kn + (size_t)64 * INW); vreg0 = *(const u32x4*)vn; vreg1 = *(const u32x4*)(vn + 64); } while (0)
; template <int DK, bool IS_A>
; __device__ __forceinline__ void attn_unit(const Params& P, int l, LAS unsigned char* lds, int b, int grp, int qtok0, int nkeys) {
;     const int tid = opaque_tid(), lane = tid & 63, wave = tid >> 6, s = wave >> 2, wq = wave & 3, r32 = lane & 31, hi = lane >> 5;
;     const bf16_t* proj = (const bf16_t*)(P.ws + WS_PROJ);
;     bf16_t* mix = (bf16_t*)(P.ws + WS_H);
;     const int qcol = IS_A ? PA_Q + grp * 64 + s * 32 : PC_Q + (2 * grp + s) * 64;
;     const int kcol = IS_A ? PA_K + grp * 64 : PC_K + grp * 64;
;     const int koff = IS_A ? s * 32 : 0;
;     const bf16_t* VT = IS_A ? (const bf16_t*)(P.ws + WS_VTA) + ((size_t)(b * 4 + grp) * 64) * TT : (const bf16_t*)(P.ws + WS_VTC) + ((size_t)(b * 2 + grp) * 64) * TT;
;     const size_t qrow = (size_t)b * TT + qtok0 + wq * 64 + r32;
;     bf16x8 qa[DK / 16], qb[DK / 16];
; #pragma unroll
;     for (int i = 0; i < DK / 16; ++i) { qa[i] = *(const bf16x8*)(proj + qrow * INW + qcol + i * 16 + hi * 8); qb[i] = *(const bf16x8*)(proj + (qrow + 32) * INW + qcol + i * 16 + hi * 8); }
;     const int lrow = tid >> 3, lch = tid & 7;
;     const bf16_t* ksrc = proj + ((size_t)b * TT + lrow) * INW + kcol + lch * 8;
;     const bf16_t* vsrc = VT + (size_t)lrow * TT + lch * 8;
;     const int NT = nkeys / AKT;
;     u32x4 kreg0, kreg1, vreg0, vreg1;
;     ...
;     const int kfo = r32 * AK_PITCH + (koff + 8 * hi) * 2, vfo = AK_BYTES + r32 * AV_PITCH + 8 * hi;
;     AT_LOAD(0); AT_STORE(0);
;     __syncthreads();
;     float ma = -1e30f, mb = -1e30f, la = 0.f, lb_ = 0.f;
;     f32x16 oa0, oa1, ob0, ob1;
; #pragma unroll
;     for (int r = 0; r < 16; ++r) { oa0[r] = 0.f; oa1[r] = 0.f; ob0[r] = 0.f; ob1[r] = 0.f; }
.LBB0_415:
	s_andn2_b64 vcc, exec, s[10:11]
	s_cbranch_vccnz .LBB0_439
	s_add_i32 s8, s37, 0xfffffe60
	s_lshr_b32 s15, s8, 5
	s_lshl_b32 s8, s37, 8
	s_and_b32 s8, s8, 0x700
	s_mul_i32 s10, s15, 0x900
	s_add_i32 s9, s8, s10
	s_lshl_b32 s8, s37, 3
	v_mov_b32_e32 v165, v200
	s_and_b32 s8, s8, 0xc0
	s_lshl_b32 s11, s15, 8
	s_or_b32 s11, s11, s8
	v_ashrrev_i32_e32 v2, 3, v165
	s_mul_i32 s64, s11, 0x900
	s_mov_b32 s11, s65
	v_ashrrev_i32_e32 v3, 31, v2
	s_addk_i32 s9, 0x100
	v_mov_b64_e32 v[0:1], s[56:57]
	s_lshl_b64 s[12:13], s[64:65], 1
	v_readlane_b32 s7, v255, 8
	v_lshl_add_u64 v[4:5], v[2:3], 0, s[10:11]
	s_add_u32 s12, s7, s12
	v_readlane_b32 s7, v255, 9
	v_mad_u64_u32 v[6:7], s[10:11], v4, s23, v[0:1]
	s_addc_u32 s13, s7, s13
	v_mad_i32_i24 v7, v5, s23, v7
	s_lshl_b32 s64, s8, 1
	v_lshlrev_b32_e32 v3, 4, v165
	v_lshl_add_u64 v[6:7], v[6:7], 0, s[64:65]
	v_and_b32_e32 v166, 0x70, v3
	v_mov_b32_e32 v167, v129
	v_lshl_add_u64 v[6:7], v[6:7], 0, v[166:167]
	s_mov_b32 s7, 0x58000
	v_mov_b64_e32 v[8:9], s[12:13]
	global_load_dwordx4 v[130:133], v[6:7], off offset:512
	v_add_co_u32_e32 v6, vcc, s7, v6
	v_mad_i64_i32 v[8:9], s[10:11], v2, s27, v[8:9]
	s_nop 0
	v_addc_co_u32_e32 v7, vcc, 0, v7, vcc
	v_lshl_add_u64 v[8:9], v[8:9], 0, v[166:167]
	global_load_dwordx4 v[134:137], v[6:7], off offset:512
	global_load_dwordx4 v[154:157], v[8:9], off
	global_load_dwordx4 v[158:161], v[8:9], off offset:128
	v_ashrrev_i32_e32 v172, 8, v165
	v_and_b32_e32 v173, 0xc0, v165
	v_and_b32_e32 v3, 31, v165
	v_lshlrev_b32_e32 v11, 5, v172
	v_add_u32_e32 v6, s8, v11
	v_or3_b32 v128, s9, v173, v3
	v_bfe_u32 v10, v165, 5, 1
	v_mad_u64_u32 v[0:1], s[10:11], v128, s23, v[0:1]
	v_ashrrev_i32_e32 v7, 31, v6
	v_lshl_add_u64 v[0:1], v[6:7], 1, v[0:1]
	v_lshlrev_b32_e32 v162, 4, v10
	v_mov_b32_e32 v163, v129
	v_lshl_add_u64 v[0:1], v[0:1], 0, v[162:163]
	s_mov_b32 s7, 0x2c000
	s_mov_b64 s[10:11], 0x2c000
	v_add_co_u32_e32 v8, vcc, s7, v0
	v_lshl_add_u64 v[6:7], v[0:1], 0, s[10:11]
	s_nop 0
	v_addc_co_u32_e32 v9, vcc, 0, v1, vcc
	global_load_dwordx4 v[138:141], v[0:1], off
	global_load_dwordx4 v[142:145], v[0:1], off offset:32
	global_load_dwordx4 v[146:149], v[8:9], off
	global_load_dwordx4 v[150:153], v[6:7], off offset:32
	s_movk_i32 s7, 0x90
	v_and_b32_e32 v0, 63, v165
	v_lshlrev_b32_e32 v164, 3, v10
	v_mul_lo_u32 v175, v2, s7
	s_movk_i32 s7, 0x108
	v_mul_lo_u32 v176, v2, s7
	v_lshlrev_b32_e32 v174, 2, v0
	v_or_b32_e32 v1, v164, v11
	v_add3_u32 v0, 0, v175, v166
	s_movk_i32 s7, 0x78
	v_mad_u64_u32 v[6:7], s[10:11], v2, s7, v[0:1]
	s_bfe_u32 s13, s37, 0x20003
	s_mul_i32 s12, s15, 0x90000
	s_mul_i32 s10, s13, 0x24000
	s_add_i32 s64, s12, s10
	s_lshl_b64 s[10:11], s[64:65], 1
	s_add_u32 s10, s54, s10
	v_lshlrev_b32_e32 v179, 1, v1
	v_add_u32_e32 v1, 0x4800, v6
	s_addc_u32 s11, s55, s11
	v_mul_u32_u24_e32 v177, 0x90, v3
	s_waitcnt vmcnt(13)
	v_mul_u32_u24_e32 v178, 0x108, v3
	v_add_u32_e32 v3, 0x4880, v6
	v_mov_b32_e32 v14, v129
	v_mov_b32_e32 v15, v129
	v_mov_b32_e32 v6, v129
	v_mov_b32_e32 v7, v129
	s_waitcnt vmcnt(7)
	ds_write_b128 v0, v[130:133]
	s_waitcnt vmcnt(6)
	ds_write_b128 v0, v[134:137] offset:9216
	s_waitcnt vmcnt(5)
	ds_write2_b64 v1, v[154:155], v[156:157] offset1:1
	s_waitcnt vmcnt(4)
	ds_write2_b64 v3, v[158:159], v[160:161] offset1:1
	v_mov_b64_e32 v[0:1], s[10:11]
	v_mad_i64_i32 v[168:169], s[10:11], v2, s27, v[0:1]
	s_lshl_b32 s10, s13, 7
	s_add_u32 s10, s54, s10
	s_addc_u32 s11, s55, 0
	v_mov_b64_e32 v[0:1], s[10:11]
	v_mad_u64_u32 v[170:171], s[10:11], v4, s23, v[0:1]
	v_mad_i32_i24 v171, v5, s23, v171
	v_mov_b32_e32 v0, v129
	v_mov_b32_e32 v1, v129
	v_mov_b32_e32 v2, v129
	v_mov_b32_e32 v3, v129
	v_mov_b32_e32 v4, v129
	v_mov_b32_e32 v5, v129
	v_mov_b32_e32 v8, v129
	v_mov_b32_e32 v9, v129
	v_mov_b32_e32 v10, v129
	v_mov_b32_e32 v11, v129
	v_mov_b32_e32 v12, v129
	v_mov_b32_e32 v13, v129
	v_mov_b64_e32 v[30:31], v[14:15]
	v_mov_b64_e32 v[46:47], v[14:15]
	v_mov_b64_e32 v[62:63], v[14:15]
	s_mov_b32 s9, 0
	v_xor_b32_e32 v163, 0x80, v174
	v_mov_b32_e32 v185, 0
	v_mov_b32_e32 v181, 0xf149f2ca
	v_mov_b32_e32 v184, 0xf149f2ca
	v_mov_b32_e32 v180, 0
	v_mov_b64_e32 v[28:29], v[12:13]
	v_mov_b64_e32 v[26:27], v[10:11]
	v_mov_b64_e32 v[24:25], v[8:9]
	v_mov_b64_e32 v[22:23], v[6:7]
	v_mov_b64_e32 v[20:21], v[4:5]
	v_mov_b64_e32 v[18:19], v[2:3]
	v_mov_b64_e32 v[16:17], v[0:1]
	v_mov_b64_e32 v[44:45], v[12:13]
	v_mov_b64_e32 v[42:43], v[10:11]
	v_mov_b64_e32 v[40:41], v[8:9]
	v_mov_b64_e32 v[38:39], v[6:7]
	v_mov_b64_e32 v[36:37], v[4:5]
	v_mov_b64_e32 v[34:35], v[2:3]
	v_mov_b64_e32 v[32:33], v[0:1]
	v_mov_b64_e32 v[60:61], v[12:13]
	v_mov_b64_e32 v[58:59], v[10:11]
	v_mov_b64_e32 v[56:57], v[8:9]
	v_mov_b64_e32 v[54:55], v[6:7]
	v_mov_b64_e32 v[52:53], v[4:5]
	v_mov_b64_e32 v[50:51], v[2:3]
	v_mov_b64_e32 v[48:49], v[0:1]
	s_waitcnt lgkmcnt(0)
	s_waitcnt vmcnt(0)
	s_mov_b32 s100, 0
	v_readfirstlane_b32 s101, v200
	s_nop 3
	s_lshr_b32 s101, s101, 8
	s_barrier
	v_mov_b32_e32 v236, 0
	v_mov_b32_e32 v237, 0
	v_mov_b32_e32 v238, 0
	v_mov_b32_e32 v239, 0
	v_mov_b32_e32 v240, 0
	v_mov_b32_e32 v241, 0
	v_mov_b32_e32 v242, 0
	v_mov_b32_e32 v243, 0
	v_mov_b32_e32 v244, 0
	v_mov_b32_e32 v245, 0
	v_mov_b32_e32 v246, 0
	v_mov_b32_e32 v247, 0
	v_mov_b32_e32 v248, 0
	v_mov_b32_e32 v249, 0
	v_mov_b32_e32 v250, 0
	v_mov_b32_e32 v251, 0
	s_branch .LBB0_418

; #define LAS __attribute__((address_space(3)))
; template <int DK, bool IS_A>
; __device__ __forceinline__ void attn_unit(const Params& P, int l, LAS unsigned char* lds, int b, int grp, int qtok0, int nkeys) {
;     ...
;             __builtin_amdgcn_s_setprio(1);
; #pragma unroll
;             for (int i = 0; i < DK / 16; ++i)
; #pragma unroll
;                 for (int jj = 0; jj < 2; ++jj) {
;                     const bf16x8 kf = *(const LAS bf16x8*)(kb + jj * 32 * AK_PITCH + i * 32);
;                     pa[jj] = __builtin_amdgcn_mfma_f32_32x32x16_bf16(kf, qa[i], pa[jj], 0, 0, 0);
;                     pb[jj] = __builtin_amdgcn_mfma_f32_32x32x16_bf16(kf, qb[i], pb[jj], 0, 0, 0);
;                 }
;             __builtin_amdgcn_s_setprio(0);
.LBB0_420:
	s_mov_b32 s12, s100
	v_add_u32_e32 v64, s12, v177
	v_add_u32_e32 v187, v64, v179
	s_setprio 1
	ds_read_b128 v[64:67], v187
	ds_read_b128 v[188:191], v187 offset:32
	s_waitcnt lgkmcnt(1)
	v_mfma_f32_32x32x16_bf16 v[112:127], v[64:67], v[138:141], v[236:251]
	v_mfma_f32_32x32x16_bf16 v[96:111], v[64:67], v[146:149], 0
	ds_read_b128 v[64:67], v187 offset:4608
	s_waitcnt lgkmcnt(1)
	v_mfma_f32_32x32x16_bf16 v[112:127], v[188:191], v[142:145], v[112:127]
	v_mfma_f32_32x32x16_bf16 v[96:111], v[188:191], v[150:153], v[96:111]
	ds_read_b128 v[188:191], v187 offset:4640
	s_waitcnt lgkmcnt(1)
	v_mfma_f32_32x32x16_bf16 v[80:95], v[64:67], v[138:141], v[236:251]
	v_mfma_f32_32x32x16_bf16 v[64:79], v[64:67], v[146:149], 0
	s_waitcnt lgkmcnt(0)
	v_mfma_f32_32x32x16_bf16 v[80:95], v[188:191], v[142:145], v[80:95]
	v_mfma_f32_32x32x16_bf16 v[64:79], v[188:191], v[150:153], v[64:79]
	s_setprio 0
	s_nop 9
	v_max_f32_e32 v182, v80, v80
	v_max_f32_e32 v183, v112, v112
	v_max_f32_e32 v182, v183, v182
	v_max3_f32 v183, v81, v114, v82
	v_max3_f32 v182, v182, v113, v115
	v_max3_f32 v183, v183, v116, v84
	v_max3_f32 v182, v182, v83, v117
	v_max3_f32 v183, v183, v118, v86
	v_max3_f32 v182, v182, v85, v119
	v_max3_f32 v183, v183, v120, v88
	v_max3_f32 v182, v182, v87, v121
	v_max3_f32 v183, v183, v122, v90
	v_max3_f32 v182, v182, v89, v123
	v_max3_f32 v183, v183, v124, v92
	v_max3_f32 v182, v182, v91, v125
	v_max3_f32 v183, v183, v126, v94
	v_max3_f32 v182, v182, v93, v127
	v_max3_f32 v182, v182, v95, v183
	v_sub_f32_e32 v182, v182, v236
	ds_bpermute_b32 v183, v163, v182
	s_waitcnt lgkmcnt(0)
	v_max3_f32 v188, v181, v182, v183
	v_add_f32_e32 v183, 0x41000000, v181
	v_cmp_gt_f32_e32 vcc, v188, v183
	s_cbranch_vccz .LBB0_422
	v_add_f32_e32 v183, v188, v236
	v_sub_f32_e32 v112, v112, v183
	v_sub_f32_e32 v113, v113, v183
	v_sub_f32_e32 v114, v114, v183
	v_sub_f32_e32 v115, v115, v183
	v_sub_f32_e32 v116, v116, v183
	v_sub_f32_e32 v117, v117, v183
	v_sub_f32_e32 v118, v118, v183
	v_sub_f32_e32 v119, v119, v183
	v_sub_f32_e32 v120, v120, v183
	v_sub_f32_e32 v121, v121, v183
	v_sub_f32_e32 v122, v122, v183
	v_sub_f32_e32 v123, v123, v183
	v_sub_f32_e32 v124, v124, v183
	v_sub_f32_e32 v125, v125, v183
	v_sub_f32_e32 v126, v126, v183
	v_sub_f32_e32 v127, v127, v183
	v_sub_f32_e32 v80, v80, v183
	v_sub_f32_e32 v81, v81, v183
	v_sub_f32_e32 v82, v82, v183
	v_sub_f32_e32 v83, v83, v183
	v_sub_f32_e32 v84, v84, v183
	v_sub_f32_e32 v85, v85, v183
	v_sub_f32_e32 v86, v86, v183
	v_sub_f32_e32 v87, v87, v183
	v_sub_f32_e32 v88, v88, v183
	v_sub_f32_e32 v89, v89, v183
	v_sub_f32_e32 v90, v90, v183
	v_sub_f32_e32 v91, v91, v183
	v_sub_f32_e32 v92, v92, v183
	v_sub_f32_e32 v93, v93, v183
	v_sub_f32_e32 v94, v94, v183
	v_sub_f32_e32 v95, v95, v183
	v_sub_f32_e32 v236, 0, v188
	v_sub_f32_e32 v237, 0, v188
	v_sub_f32_e32 v238, 0, v188
	v_sub_f32_e32 v239, 0, v188
	v_sub_f32_e32 v240, 0, v188
	v_sub_f32_e32 v241, 0, v188
	v_sub_f32_e32 v242, 0, v188
	v_sub_f32_e32 v243, 0, v188
	v_sub_f32_e32 v244, 0, v188
	v_sub_f32_e32 v245, 0, v188
	v_sub_f32_e32 v246, 0, v188
	v_sub_f32_e32 v247, 0, v188
	v_sub_f32_e32 v248, 0, v188
	v_sub_f32_e32 v249, 0, v188
	v_sub_f32_e32 v250, 0, v188
	v_sub_f32_e32 v251, 0, v188
	v_sub_f32_e32 v181, v181, v188
	v_exp_f32_e32 v182, v181
	s_nop 0
	v_pk_mul_f32 v[62:63], v[62:63], v[182:183] op_sel_hi:[1,0]
	v_pk_mul_f32 v[60:61], v[60:61], v[182:183] op_sel_hi:[1,0]
	v_pk_mul_f32 v[58:59], v[58:59], v[182:183] op_sel_hi:[1,0]
	v_pk_mul_f32 v[56:57], v[56:57], v[182:183] op_sel_hi:[1,0]
	v_pk_mul_f32 v[54:55], v[54:55], v[182:183] op_sel_hi:[1,0]
	v_pk_mul_f32 v[52:53], v[52:53], v[182:183] op_sel_hi:[1,0]
	v_pk_mul_f32 v[50:51], v[50:51], v[182:183] op_sel_hi:[1,0]
	v_pk_mul_f32 v[48:49], v[48:49], v[182:183] op_sel_hi:[1,0]
	v_pk_mul_f32 v[46:47], v[46:47], v[182:183] op_sel_hi:[1,0]
	v_pk_mul_f32 v[44:45], v[44:45], v[182:183] op_sel_hi:[1,0]
	v_pk_mul_f32 v[42:43], v[42:43], v[182:183] op_sel_hi:[1,0]
	v_pk_mul_f32 v[40:41], v[40:41], v[182:183] op_sel_hi:[1,0]
	v_pk_mul_f32 v[38:39], v[38:39], v[182:183] op_sel_hi:[1,0]
	v_pk_mul_f32 v[36:37], v[36:37], v[182:183] op_sel_hi:[1,0]
	v_pk_mul_f32 v[34:35], v[34:35], v[182:183] op_sel_hi:[1,0]
	v_pk_mul_f32 v[32:33], v[32:33], v[182:183] op_sel_hi:[1,0]
	v_mul_f32_e32 v185, v185, v182
	s_branch .LBB0_423

; #define LAS __attribute__((address_space(3)))
; __device__ __forceinline__ unsigned pk2(float lo, float hi) { f32x2_t v = {lo, hi}; bf16x2_t b = __builtin_convertvector(v, bf16x2_t); return __builtin_bit_cast(unsigned, b); }
; template <int DK, bool IS_A>
; __device__ __forceinline__ void attn_unit(const Params& P, int l, LAS unsigned char* lds, int b, int grp, int qtok0, int nkeys) {
;     ...
;             AT_SOFTMAX(pa, ma, la, oa0, oa1);
;             AT_SOFTMAX(pb, mb, lb_, ob0, ob1);
;     ...
; #pragma unroll
;             for (int ks = 0; ks < 4; ++ks) {
;                 const int o8 = 8 * (ks & 1);
;                 u32x4 w; const f32x16& xa = pa[ks >> 1]; const f32x16& xb = pb[ks >> 1];
;                 w.x = pk2(xa[o8], xa[o8 + 1]); w.y = pk2(xa[o8 + 2], xa[o8 + 3]); w.z = pk2(xa[o8 + 4], xa[o8 + 5]); w.w = pk2(xa[o8 + 6], xa[o8 + 7]);
;                 const bf16x8 pfa = __builtin_bit_cast(bf16x8, w);
;                 w.x = pk2(xb[o8], xb[o8 + 1]); w.y = pk2(xb[o8 + 2], xb[o8 + 3]); w.z = pk2(xb[o8 + 4], xb[o8 + 5]); w.w = pk2(xb[o8 + 6], xb[o8 + 7]);
;                 const bf16x8 pfb = __builtin_bit_cast(bf16x8, w);
;                 const u32x2 a0 = *(const LAS u32x2*)(vb + ks * 32), a1 = *(const LAS u32x2*)(vb + ks * 32 + 16);
;                 const u32x2 c0 = *(const LAS u32x2*)(vb + 32 * AV_PITCH + ks * 32), c1 = *(const LAS u32x2*)(vb + 32 * AV_PITCH + ks * 32 + 16);
;                 const bf16x8 v0 = __builtin_bit_cast(bf16x8, ((u32x4){a0.x, a0.y, a1.x, a1.y})), v1 = __builtin_bit_cast(bf16x8, ((u32x4){c0.x, c0.y, c1.x, c1.y}));
;                 oa0 = __builtin_amdgcn_mfma_f32_32x32x16_bf16(v0, pfa, oa0, 0, 0, 0);
;                 oa1 = __builtin_amdgcn_mfma_f32_32x32x16_bf16(v1, pfa, oa1, 0, 0, 0);
;                 ob0 = __builtin_amdgcn_mfma_f32_32x32x16_bf16(v0, pfb, ob0, 0, 0, 0);
;                 ob1 = __builtin_amdgcn_mfma_f32_32x32x16_bf16(v1, pfb, ob1, 0, 0, 0);
;             }
.LBB0_426:
	v_exp_f32_e32 v112, v112
	v_exp_f32_e32 v113, v113
	v_exp_f32_e32 v114, v114
	v_exp_f32_e32 v115, v115
	v_add_f32_e32 v181, 0, v112
	v_exp_f32_e32 v116, v116
	v_add_f32_e32 v181, v113, v181
	v_exp_f32_e32 v117, v117
	v_add_f32_e32 v181, v114, v181
	v_exp_f32_e32 v118, v118
	v_add_f32_e32 v181, v115, v181
	v_exp_f32_e32 v119, v119
	v_add_f32_e32 v181, v116, v181
	v_exp_f32_e32 v120, v120
	v_add_f32_e32 v181, v117, v181
	v_exp_f32_e32 v121, v121
	v_add_f32_e32 v181, v118, v181
	v_exp_f32_e32 v122, v122
	v_add_f32_e32 v181, v119, v181
	v_exp_f32_e32 v123, v123
	v_add_f32_e32 v181, v120, v181
	v_exp_f32_e32 v124, v124
	v_add_f32_e32 v181, v121, v181
	v_exp_f32_e32 v125, v125
	v_add_f32_e32 v181, v122, v181
	v_exp_f32_e32 v126, v126
	v_add_f32_e32 v181, v123, v181
	v_exp_f32_e32 v127, v127
	v_add_f32_e32 v181, v124, v181
	v_exp_f32_e32 v211, v80
	v_add_f32_e32 v181, v125, v181
	v_exp_f32_e32 v212, v81
	v_add_f32_e32 v80, v126, v181
	v_exp_f32_e32 v181, v82
	v_add_f32_e32 v80, v127, v80
	v_exp_f32_e32 v213, v83
	v_add_f32_e32 v80, v211, v80
	v_exp_f32_e32 v214, v84
	v_add_f32_e32 v80, v212, v80
	v_exp_f32_e32 v215, v85
	v_add_f32_e32 v80, v181, v80
	v_exp_f32_e32 v216, v86
	v_add_f32_e32 v80, v213, v80
	v_exp_f32_e32 v217, v87
	v_add_f32_e32 v80, v214, v80
	v_exp_f32_e32 v218, v88
	v_add_f32_e32 v80, v215, v80
	v_exp_f32_e32 v220, v89
	v_add_f32_e32 v80, v216, v80
	v_add_f32_e32 v80, v217, v80
	v_add_f32_e32 v80, v218, v80
	v_add_f32_e32 v224, v220, v80
	v_exp_f32_e32 v225, v90
	v_exp_f32_e32 v226, v91
	v_exp_f32_e32 v92, v92
	v_add_u32_e32 v80, s12, v178
	v_sub_f32_e32 v81, v96, v186
	v_add_u32_e32 v88, v80, v164
	v_exp_f32_e32 v184, v81
	v_sub_f32_e32 v81, v97, v186
	v_add_u32_e32 v182, 0x4800, v88
	v_add_u32_e32 v183, 0x6800, v88
	v_exp_f32_e32 v189, v81
	ds_read2_b64 v[80:83], v182 offset1:2
	ds_read2_b64 v[88:91], v183 offset0:32 offset1:34
	v_sub_f32_e32 v96, v99, v186
	v_sub_f32_e32 v84, v98, v186
	v_exp_f32_e32 v191, v96
	v_sub_f32_e32 v96, v100, v186
	v_exp_f32_e32 v190, v84
	v_cvt_pk_bf16_f32 v84, v112, v113
	v_cvt_pk_bf16_f32 v85, v114, v115
	v_cvt_pk_bf16_f32 v86, v116, v117
	v_cvt_pk_bf16_f32 v87, v118, v119
	v_exp_f32_e32 v192, v96
	v_sub_f32_e32 v96, v101, v186
	s_waitcnt lgkmcnt(1)
	v_mfma_f32_32x32x16_bf16 v[48:63], v[80:83], v[84:87], v[48:63]
	v_exp_f32_e32 v193, v96
	v_sub_f32_e32 v96, v102, v186
	v_exp_f32_e32 v194, v96
	v_sub_f32_e32 v96, v107, v186
	v_exp_f32_e32 v199, v96
	v_sub_f32_e32 v96, v108, v186
	v_exp_f32_e32 v204, v96
	s_waitcnt lgkmcnt(0)
	v_mfma_f32_32x32x16_bf16 v[32:47], v[88:91], v[84:87], v[32:47]
	v_sub_f32_e32 v84, v103, v186
	v_exp_f32_e32 v195, v84
	v_cvt_pk_bf16_f32 v84, v184, v189
	v_cvt_pk_bf16_f32 v85, v190, v191
	v_cvt_pk_bf16_f32 v86, v192, v193
	v_cvt_pk_bf16_f32 v87, v194, v195
	v_sub_f32_e32 v96, v109, v186
	v_exp_f32_e32 v205, v96
	v_mfma_f32_32x32x16_bf16 v[16:31], v[80:83], v[84:87], v[16:31]
	v_exp_f32_e32 v93, v93
	v_sub_f32_e32 v80, v104, v186
	v_exp_f32_e32 v196, v80
	v_sub_f32_e32 v80, v105, v186
	v_exp_f32_e32 v197, v80
	ds_read2_b64 v[80:83], v182 offset0:4 offset1:6
	v_mfma_f32_32x32x16_bf16 v[0:15], v[88:91], v[84:87], v[0:15]
	ds_read2_b64 v[88:91], v183 offset0:36 offset1:38
	v_sub_f32_e32 v84, v106, v186
	v_exp_f32_e32 v198, v84
	v_cvt_pk_bf16_f32 v84, v120, v121
	v_cvt_pk_bf16_f32 v85, v122, v123
	v_cvt_pk_bf16_f32 v86, v124, v125
	v_cvt_pk_bf16_f32 v87, v126, v127
	v_sub_f32_e32 v96, v110, v186
	v_exp_f32_e32 v206, v96
	s_waitcnt lgkmcnt(1)
	v_mfma_f32_32x32x16_bf16 v[48:63], v[80:83], v[84:87], v[48:63]
	v_sub_f32_e32 v64, v64, v186
	v_exp_f32_e32 v208, v64
	v_sub_f32_e32 v64, v65, v186
	v_exp_f32_e32 v209, v64
	v_sub_f32_e32 v64, v66, v186
	v_exp_f32_e32 v210, v64
	v_sub_f32_e32 v64, v67, v186
	s_waitcnt lgkmcnt(0)
	v_mfma_f32_32x32x16_bf16 v[32:47], v[88:91], v[84:87], v[32:47]
	v_sub_f32_e32 v84, v111, v186
	v_exp_f32_e32 v207, v84
	v_cvt_pk_bf16_f32 v84, v196, v197
	v_cvt_pk_bf16_f32 v85, v198, v199
	v_cvt_pk_bf16_f32 v86, v204, v205
	v_cvt_pk_bf16_f32 v87, v206, v207
	s_nop 1
	s_nop 1
	v_mfma_f32_32x32x16_bf16 v[16:31], v[80:83], v[84:87], v[16:31]
	v_exp_f32_e32 v94, v94
	ds_read2_b64 v[80:83], v182 offset0:8 offset1:10
	v_mfma_f32_32x32x16_bf16 v[0:15], v[88:91], v[84:87], v[0:15]
	ds_read2_b64 v[88:91], v183 offset0:40 offset1:42
	v_cvt_pk_bf16_f32 v84, v211, v212
	v_exp_f32_e32 v211, v64
	v_sub_f32_e32 v64, v68, v186
	v_exp_f32_e32 v212, v64
	v_sub_f32_e32 v64, v69, v186
	v_cvt_pk_bf16_f32 v85, v181, v213
	v_exp_f32_e32 v213, v64
	v_sub_f32_e32 v64, v70, v186
	v_cvt_pk_bf16_f32 v86, v214, v215
	v_exp_f32_e32 v214, v64
	v_sub_f32_e32 v64, v71, v186
	v_exp_f32_e32 v215, v64
	v_cvt_pk_bf16_f32 v87, v216, v217
	v_cvt_pk_bf16_f32 v64, v208, v209
	s_waitcnt lgkmcnt(1)
	v_mfma_f32_32x32x16_bf16 v[48:63], v[80:83], v[84:87], v[48:63]
	v_cvt_pk_bf16_f32 v65, v210, v211
	v_cvt_pk_bf16_f32 v66, v212, v213
	v_cvt_pk_bf16_f32 v67, v214, v215
	s_waitcnt lgkmcnt(0)
	v_mfma_f32_32x32x16_bf16 v[32:47], v[88:91], v[84:87], v[32:47]
	v_exp_f32_e32 v84, v95
	v_sub_f32_e32 v68, v72, v186
	v_exp_f32_e32 v216, v68
	v_sub_f32_e32 v68, v73, v186
	v_exp_f32_e32 v217, v68
	ds_read2_b64 v[68:71], v182 offset0:12 offset1:14
	v_sub_f32_e32 v72, v75, v186
	v_mfma_f32_32x32x16_bf16 v[16:31], v[80:83], v[64:67], v[16:31]
	ds_read2_b64 v[80:83], v183 offset0:44 offset1:46
	v_exp_f32_e32 v222, v72
	v_sub_f32_e32 v72, v76, v186
	v_exp_f32_e32 v223, v72
	v_sub_f32_e32 v72, v77, v186
	v_mfma_f32_32x32x16_bf16 v[0:15], v[88:91], v[64:67], v[0:15]
	v_sub_f32_e32 v64, v74, v186
	v_exp_f32_e32 v219, v64
	v_cvt_pk_bf16_f32 v64, v218, v220
	v_cvt_pk_bf16_f32 v65, v225, v226
	v_cvt_pk_bf16_f32 v66, v92, v93
	v_cvt_pk_bf16_f32 v67, v94, v84
	v_exp_f32_e32 v218, v72
	v_sub_f32_e32 v72, v78, v186
	s_waitcnt lgkmcnt(1)
; #define LAS __attribute__((address_space(3)))
; __device__ __forceinline__ unsigned pk2(float lo, float hi) { f32x2_t v = {lo, hi}; bf16x2_t b = __builtin_convertvector(v, bf16x2_t); return __builtin_bit_cast(unsigned, b); }
; template <int DK, bool IS_A>
; __device__ __forceinline__ void attn_unit(const Params& P, int l, LAS unsigned char* lds, int b, int grp, int qtok0, int nkeys) {
;     ...
;             __builtin_amdgcn_s_setprio(1);
; #pragma unroll
;             for (int i = 0; i < DK / 16; ++i)
; #pragma unroll
;                 for (int jj = 0; jj < 2; ++jj) {
;                     const bf16x8 kf = *(const LAS bf16x8*)(kb + jj * 32 * AK_PITCH + i * 32);
;                     pa[jj] = __builtin_amdgcn_mfma_f32_32x32x16_bf16(kf, qa[i], pa[jj], 0, 0, 0);
;                     pb[jj] = __builtin_amdgcn_mfma_f32_32x32x16_bf16(kf, qb[i], pb[jj], 0, 0, 0);
;                 }
;             __builtin_amdgcn_s_setprio(0);
;     ...
;             for (int ks = 0; ks < 4; ++ks) {
;                 const int o8 = 8 * (ks & 1);
;                 u32x4 w; const f32x16& xa = pa[ks >> 1]; const f32x16& xb = pb[ks >> 1];
;                 w.x = pk2(xa[o8], xa[o8 + 1]); w.y = pk2(xa[o8 + 2], xa[o8 + 3]); w.z = pk2(xa[o8 + 4], xa[o8 + 5]); w.w = pk2(xa[o8 + 6], xa[o8 + 7]);
;                 const bf16x8 pfa = __builtin_bit_cast(bf16x8, w);
;                 w.x = pk2(xb[o8], xb[o8 + 1]); w.y = pk2(xb[o8 + 2], xb[o8 + 3]); w.z = pk2(xb[o8 + 4], xb[o8 + 5]); w.w = pk2(xb[o8 + 6], xb[o8 + 7]);
;                 const bf16x8 pfb = __builtin_bit_cast(bf16x8, w);
;                 const u32x2 a0 = *(const LAS u32x2*)(vb + ks * 32), a1 = *(const LAS u32x2*)(vb + ks * 32 + 16);
;                 const u32x2 c0 = *(const LAS u32x2*)(vb + 32 * AV_PITCH + ks * 32), c1 = *(const LAS u32x2*)(vb + 32 * AV_PITCH + ks * 32 + 16);
;                 const bf16x8 v0 = __builtin_bit_cast(bf16x8, ((u32x4){a0.x, a0.y, a1.x, a1.y})), v1 = __builtin_bit_cast(bf16x8, ((u32x4){c0.x, c0.y, c1.x, c1.y}));
;                 oa0 = __builtin_amdgcn_mfma_f32_32x32x16_bf16(v0, pfa, oa0, 0, 0, 0);
;                 oa1 = __builtin_amdgcn_mfma_f32_32x32x16_bf16(v1, pfa, oa1, 0, 0, 0);
;                 ob0 = __builtin_amdgcn_mfma_f32_32x32x16_bf16(v0, pfb, ob0, 0, 0, 0);
;                 ob1 = __builtin_amdgcn_mfma_f32_32x32x16_bf16(v1, pfb, ob1, 0, 0, 0);
;             }
	v_mfma_f32_32x32x16_bf16 v[48:63], v[68:71], v[64:67], v[48:63]
	v_exp_f32_e32 v220, v72
	s_waitcnt lgkmcnt(0)
	v_mfma_f32_32x32x16_bf16 v[32:47], v[80:83], v[64:67], v[32:47]
	v_sub_f32_e32 v64, v79, v186
	v_exp_f32_e32 v221, v64
	v_cvt_pk_bf16_f32 v64, v216, v217
	v_cvt_pk_bf16_f32 v65, v219, v222
	v_cvt_pk_bf16_f32 v66, v223, v218
	v_cvt_pk_bf16_f32 v67, v220, v221
	s_nop 1
	s_nop 1
	v_mfma_f32_32x32x16_bf16 v[16:31], v[68:71], v[64:67], v[16:31]
	v_add_f32_e32 v68, v225, v224
	v_add_f32_e32 v68, v226, v68
	v_add_f32_e32 v68, v92, v68
	v_add_f32_e32 v68, v93, v68
	v_add_f32_e32 v68, v94, v68
	v_add_f32_e32 v68, v84, v68
	v_add_f32_e32 v185, v185, v68
	v_mfma_f32_32x32x16_bf16 v[0:15], v[80:83], v[64:67], v[0:15]
	s_setprio 1
	ds_read_b128 v[64:67], v187 offset:9216
	ds_read_b128 v[224:227], v187 offset:9248
	s_waitcnt lgkmcnt(1)
	v_mfma_f32_32x32x16_bf16 v[112:127], v[64:67], v[138:141], v[236:251]
	v_mfma_f32_32x32x16_bf16 v[96:111], v[64:67], v[146:149], 0
	ds_read_b128 v[64:67], v187 offset:13824
	s_waitcnt lgkmcnt(1)
	v_mfma_f32_32x32x16_bf16 v[112:127], v[224:227], v[142:145], v[112:127]
	v_mfma_f32_32x32x16_bf16 v[96:111], v[224:227], v[150:153], v[96:111]
	ds_read_b128 v[224:227], v187 offset:13856
	s_waitcnt lgkmcnt(1)
	v_mfma_f32_32x32x16_bf16 v[80:95], v[64:67], v[138:141], v[236:251]
	v_mfma_f32_32x32x16_bf16 v[64:79], v[64:67], v[146:149], 0
	s_waitcnt lgkmcnt(0)
	v_mfma_f32_32x32x16_bf16 v[80:95], v[224:227], v[142:145], v[80:95]
	v_mfma_f32_32x32x16_bf16 v[64:79], v[224:227], v[150:153], v[64:79]
	s_setprio 0
	s_nop 9
	v_max_f32_e32 v181, v80, v80
	v_max_f32_e32 v187, v112, v112
	v_max_f32_e32 v181, v187, v181
	v_max3_f32 v187, v81, v114, v82
	v_max3_f32 v181, v181, v113, v115
	v_max3_f32 v187, v187, v116, v84
	v_max3_f32 v181, v181, v83, v117
	v_max3_f32 v187, v187, v118, v86
	v_max3_f32 v181, v181, v85, v119
	v_max3_f32 v187, v187, v120, v88
	v_max3_f32 v181, v181, v87, v121
	v_max3_f32 v187, v187, v122, v90
	v_max3_f32 v181, v181, v89, v123
	v_max3_f32 v187, v187, v124, v92
	v_max3_f32 v181, v181, v91, v125
	v_max3_f32 v187, v187, v126, v94
	v_max3_f32 v181, v181, v93, v127
	v_max3_f32 v181, v181, v95, v187
	v_sub_f32_e32 v181, v181, v236
	ds_bpermute_b32 v187, v163, v181
	s_waitcnt lgkmcnt(0)
	v_max3_f32 v181, v188, v181, v187
	v_add_f32_e32 v187, 0x41000000, v188
	v_cmp_gt_f32_e32 vcc, v181, v187
	s_cbranch_vccz .LBB0_428
	v_add_f32_e32 v187, v181, v236
	v_sub_f32_e32 v112, v112, v187
	v_sub_f32_e32 v113, v113, v187
	v_sub_f32_e32 v114, v114, v187
	v_sub_f32_e32 v115, v115, v187
	v_sub_f32_e32 v116, v116, v187
	v_sub_f32_e32 v117, v117, v187
	v_sub_f32_e32 v118, v118, v187
	v_sub_f32_e32 v119, v119, v187
	v_sub_f32_e32 v120, v120, v187
	v_sub_f32_e32 v121, v121, v187
	v_sub_f32_e32 v122, v122, v187
	v_sub_f32_e32 v123, v123, v187
	v_sub_f32_e32 v124, v124, v187
	v_sub_f32_e32 v125, v125, v187
	v_sub_f32_e32 v126, v126, v187
	v_sub_f32_e32 v127, v127, v187
	v_sub_f32_e32 v80, v80, v187
	v_sub_f32_e32 v81, v81, v187
	v_sub_f32_e32 v82, v82, v187
	v_sub_f32_e32 v83, v83, v187
	v_sub_f32_e32 v84, v84, v187
	v_sub_f32_e32 v85, v85, v187
	v_sub_f32_e32 v86, v86, v187
	v_sub_f32_e32 v87, v87, v187
	v_sub_f32_e32 v88, v88, v187
	v_sub_f32_e32 v89, v89, v187
	v_sub_f32_e32 v90, v90, v187
	v_sub_f32_e32 v91, v91, v187
	v_sub_f32_e32 v92, v92, v187
	v_sub_f32_e32 v93, v93, v187
	v_sub_f32_e32 v94, v94, v187
	v_sub_f32_e32 v95, v95, v187
	v_sub_f32_e32 v236, 0, v181
	v_sub_f32_e32 v237, 0, v181
	v_sub_f32_e32 v238, 0, v181
	v_sub_f32_e32 v239, 0, v181
	v_sub_f32_e32 v240, 0, v181
	v_sub_f32_e32 v241, 0, v181
	v_sub_f32_e32 v242, 0, v181
	v_sub_f32_e32 v243, 0, v181
	v_sub_f32_e32 v244, 0, v181
	v_sub_f32_e32 v245, 0, v181
	v_sub_f32_e32 v246, 0, v181
	v_sub_f32_e32 v247, 0, v181
	v_sub_f32_e32 v248, 0, v181
	v_sub_f32_e32 v249, 0, v181
	v_sub_f32_e32 v250, 0, v181
	v_sub_f32_e32 v251, 0, v181
	v_sub_f32_e32 v187, v188, v181
	v_exp_f32_e32 v188, v187
	s_nop 0
	v_pk_mul_f32 v[62:63], v[62:63], v[188:189] op_sel_hi:[1,0]
	v_pk_mul_f32 v[60:61], v[60:61], v[188:189] op_sel_hi:[1,0]
	v_pk_mul_f32 v[58:59], v[58:59], v[188:189] op_sel_hi:[1,0]
	v_pk_mul_f32 v[56:57], v[56:57], v[188:189] op_sel_hi:[1,0]
	v_pk_mul_f32 v[54:55], v[54:55], v[188:189] op_sel_hi:[1,0]
	v_pk_mul_f32 v[52:53], v[52:53], v[188:189] op_sel_hi:[1,0]
	v_pk_mul_f32 v[50:51], v[50:51], v[188:189] op_sel_hi:[1,0]
	v_pk_mul_f32 v[48:49], v[48:49], v[188:189] op_sel_hi:[1,0]
	v_pk_mul_f32 v[46:47], v[46:47], v[188:189] op_sel_hi:[1,0]
	v_pk_mul_f32 v[44:45], v[44:45], v[188:189] op_sel_hi:[1,0]
	v_pk_mul_f32 v[42:43], v[42:43], v[188:189] op_sel_hi:[1,0]
	v_pk_mul_f32 v[40:41], v[40:41], v[188:189] op_sel_hi:[1,0]
	v_pk_mul_f32 v[38:39], v[38:39], v[188:189] op_sel_hi:[1,0]
	v_pk_mul_f32 v[36:37], v[36:37], v[188:189] op_sel_hi:[1,0]
	v_pk_mul_f32 v[34:35], v[34:35], v[188:189] op_sel_hi:[1,0]
	v_pk_mul_f32 v[32:33], v[32:33], v[188:189] op_sel_hi:[1,0]
	v_mul_f32_e32 v185, v185, v188
	s_branch .LBB0_429

; #define LAS __attribute__((address_space(3)))
; __device__ __forceinline__ unsigned pk2(float lo, float hi) { f32x2_t v = {lo, hi}; bf16x2_t b = __builtin_convertvector(v, bf16x2_t); return __builtin_bit_cast(unsigned, b); }
; template <int DK, bool IS_A>
; __device__ __forceinline__ void attn_unit(const Params& P, int l, LAS unsigned char* lds, int b, int grp, int qtok0, int nkeys) {
;     ...
;             AT_SOFTMAX(pa, ma, la, oa0, oa1);
;             AT_SOFTMAX(pb, mb, lb_, ob0, ob1);
;     ...
; #pragma unroll
;             for (int ks = 0; ks < 4; ++ks) {
;                 const int o8 = 8 * (ks & 1);
;                 u32x4 w; const f32x16& xa = pa[ks >> 1]; const f32x16& xb = pb[ks >> 1];
;                 w.x = pk2(xa[o8], xa[o8 + 1]); w.y = pk2(xa[o8 + 2], xa[o8 + 3]); w.z = pk2(xa[o8 + 4], xa[o8 + 5]); w.w = pk2(xa[o8 + 6], xa[o8 + 7]);
;                 const bf16x8 pfa = __builtin_bit_cast(bf16x8, w);
;                 w.x = pk2(xb[o8], xb[o8 + 1]); w.y = pk2(xb[o8 + 2], xb[o8 + 3]); w.z = pk2(xb[o8 + 4], xb[o8 + 5]); w.w = pk2(xb[o8 + 6], xb[o8 + 7]);
;                 const bf16x8 pfb = __builtin_bit_cast(bf16x8, w);
;                 const u32x2 a0 = *(const LAS u32x2*)(vb + ks * 32), a1 = *(const LAS u32x2*)(vb + ks * 32 + 16);
;                 const u32x2 c0 = *(const LAS u32x2*)(vb + 32 * AV_PITCH + ks * 32), c1 = *(const LAS u32x2*)(vb + 32 * AV_PITCH + ks * 32 + 16);
;                 const bf16x8 v0 = __builtin_bit_cast(bf16x8, ((u32x4){a0.x, a0.y, a1.x, a1.y})), v1 = __builtin_bit_cast(bf16x8, ((u32x4){c0.x, c0.y, c1.x, c1.y}));
;                 oa0 = __builtin_amdgcn_mfma_f32_32x32x16_bf16(v0, pfa, oa0, 0, 0, 0);
;                 oa1 = __builtin_amdgcn_mfma_f32_32x32x16_bf16(v1, pfa, oa1, 0, 0, 0);
;                 ob0 = __builtin_amdgcn_mfma_f32_32x32x16_bf16(v0, pfb, ob0, 0, 0, 0);
;                 ob1 = __builtin_amdgcn_mfma_f32_32x32x16_bf16(v1, pfb, ob1, 0, 0, 0);
;             }
;         }
;         if (t + 1 < NT) AT_STORE(buf ^ 1);
;         __syncthreads();
;     }
.Latta_w03:
	ds_read2_b64 v[186:189], v182 offset0:16 offset1:18
	ds_read2_b64 v[194:197], v183 offset0:48 offset1:50
	v_exp_f32_e32 v112, v112
	v_exp_f32_e32 v113, v113
	v_exp_f32_e32 v114, v114
	v_exp_f32_e32 v115, v115
	v_exp_f32_e32 v116, v116
	v_exp_f32_e32 v117, v117
	v_exp_f32_e32 v118, v118
	v_exp_f32_e32 v119, v119
	v_sub_f32_e32 v96, v96, v184
	v_sub_f32_e32 v97, v97, v184
	v_sub_f32_e32 v98, v98, v184
	v_sub_f32_e32 v99, v99, v184
	v_sub_f32_e32 v100, v100, v184
	v_sub_f32_e32 v101, v101, v184
	v_sub_f32_e32 v102, v102, v184
	v_sub_f32_e32 v103, v103, v184
	v_exp_f32_e32 v96, v96
	v_exp_f32_e32 v97, v97
	v_exp_f32_e32 v98, v98
	v_exp_f32_e32 v99, v99
	v_exp_f32_e32 v100, v100
	v_exp_f32_e32 v101, v101
	v_exp_f32_e32 v102, v102
	v_exp_f32_e32 v103, v103
	v_cvt_pk_bf16_f32 v190, v112, v113
	v_cvt_pk_bf16_f32 v191, v114, v115
	v_cvt_pk_bf16_f32 v192, v116, v117
	v_cvt_pk_bf16_f32 v193, v118, v119
	s_waitcnt lgkmcnt(1)
	s_nop 1
	v_mfma_f32_32x32x16_bf16 v[48:63], v[186:189], v[190:193], v[48:63]
	v_exp_f32_e32 v120, v120
	s_waitcnt lgkmcnt(0)
	v_mfma_f32_32x32x16_bf16 v[32:47], v[194:197], v[190:193], v[32:47]
	v_cvt_pk_bf16_f32 v190, v96, v97
	v_cvt_pk_bf16_f32 v191, v98, v99
	v_cvt_pk_bf16_f32 v192, v100, v101
	v_cvt_pk_bf16_f32 v193, v102, v103
	v_exp_f32_e32 v121, v121
	v_exp_f32_e32 v122, v122
	v_exp_f32_e32 v123, v123
	v_mfma_f32_32x32x16_bf16 v[16:31], v[186:189], v[190:193], v[16:31]
	ds_read2_b64 v[186:189], v182 offset0:20 offset1:22
	v_exp_f32_e32 v124, v124
	v_exp_f32_e32 v125, v125
	v_exp_f32_e32 v126, v126
	v_exp_f32_e32 v127, v127
	v_sub_f32_e32 v104, v104, v184
	v_sub_f32_e32 v105, v105, v184
	v_mfma_f32_32x32x16_bf16 v[0:15], v[194:197], v[190:193], v[0:15]
	ds_read2_b64 v[194:197], v183 offset0:52 offset1:54
	v_sub_f32_e32 v106, v106, v184
	v_sub_f32_e32 v107, v107, v184
	v_sub_f32_e32 v108, v108, v184
	v_sub_f32_e32 v109, v109, v184
	v_sub_f32_e32 v110, v110, v184
	v_sub_f32_e32 v111, v111, v184
	v_exp_f32_e32 v104, v104
	v_exp_f32_e32 v105, v105
	v_exp_f32_e32 v106, v106
	v_exp_f32_e32 v107, v107
	v_exp_f32_e32 v108, v108
	v_exp_f32_e32 v109, v109
	v_exp_f32_e32 v110, v110
	v_exp_f32_e32 v111, v111
	v_cvt_pk_bf16_f32 v190, v120, v121
	v_cvt_pk_bf16_f32 v191, v122, v123
	v_cvt_pk_bf16_f32 v192, v124, v125
	v_cvt_pk_bf16_f32 v193, v126, v127
	v_sub_f32_e32 v66, v66, v184
	ds_read2_b64 v[204:207], v182 offset0:24 offset1:26
	s_waitcnt lgkmcnt(2)
	v_mfma_f32_32x32x16_bf16 v[48:63], v[186:189], v[190:193], v[48:63]
	s_waitcnt lgkmcnt(1)
	v_mfma_f32_32x32x16_bf16 v[32:47], v[194:197], v[190:193], v[32:47]
	v_cvt_pk_bf16_f32 v190, v104, v105
	v_cvt_pk_bf16_f32 v191, v106, v107
	v_cvt_pk_bf16_f32 v192, v108, v109
	v_cvt_pk_bf16_f32 v193, v110, v111
	v_exp_f32_e32 v80, v80
	v_exp_f32_e32 v81, v81
	v_mfma_f32_32x32x16_bf16 v[16:31], v[186:189], v[190:193], v[16:31]
	v_exp_f32_e32 v186, v66
	v_sub_f32_e32 v66, v67, v184
	v_exp_f32_e32 v67, v66
	v_sub_f32_e32 v66, v68, v184
	v_exp_f32_e32 v68, v66
	v_sub_f32_e32 v66, v69, v184
	v_exp_f32_e32 v69, v66
	v_mfma_f32_32x32x16_bf16 v[0:15], v[194:197], v[190:193], v[0:15]
	ds_read2_b64 v[192:195], v183 offset0:56 offset1:58
	v_sub_f32_e32 v66, v70, v184
	v_exp_f32_e32 v82, v82
	v_exp_f32_e32 v83, v83
	v_exp_f32_e32 v84, v84
	v_exp_f32_e32 v85, v85
	v_exp_f32_e32 v86, v86
	v_exp_f32_e32 v87, v87
	v_sub_f32_e32 v64, v64, v184
	v_sub_f32_e32 v65, v65, v184
	v_exp_f32_e32 v70, v66
	v_sub_f32_e32 v66, v71, v184
	v_exp_f32_e32 v64, v64
	v_exp_f32_e32 v65, v65
	v_exp_f32_e32 v71, v66
	v_cvt_pk_bf16_f32 v188, v80, v81
	v_cvt_pk_bf16_f32 v189, v82, v83
	v_cvt_pk_bf16_f32 v190, v84, v85
	v_cvt_pk_bf16_f32 v191, v86, v87
	ds_read2_b64 v[196:199], v182 offset0:28 offset1:30
	s_waitcnt lgkmcnt(2)
	v_mfma_f32_32x32x16_bf16 v[48:63], v[204:207], v[188:191], v[48:63]
	s_waitcnt lgkmcnt(1)
	v_mfma_f32_32x32x16_bf16 v[32:47], v[192:195], v[188:191], v[32:47]
	v_cvt_pk_bf16_f32 v188, v64, v65
	v_cvt_pk_bf16_f32 v189, v186, v67
	v_cvt_pk_bf16_f32 v190, v68, v69
	v_cvt_pk_bf16_f32 v191, v70, v71
	v_exp_f32_e32 v88, v88
	v_exp_f32_e32 v89, v89
	v_exp_f32_e32 v90, v90
	v_mfma_f32_32x32x16_bf16 v[0:15], v[192:195], v[188:191], v[0:15]
	ds_read2_b64 v[192:195], v183 offset0:60 offset1:62
	v_exp_f32_e32 v91, v91
	v_exp_f32_e32 v92, v92
	v_exp_f32_e32 v93, v93
	v_exp_f32_e32 v94, v94
	v_exp_f32_e32 v66, v95
	v_sub_f32_e32 v72, v72, v184
	v_mfma_f32_32x32x16_bf16 v[16:31], v[204:207], v[188:191], v[16:31]
	v_sub_f32_e32 v73, v73, v184
	v_sub_f32_e32 v74, v74, v184
	v_sub_f32_e32 v75, v75, v184
	v_sub_f32_e32 v76, v76, v184
	v_sub_f32_e32 v77, v77, v184
	v_sub_f32_e32 v78, v78, v184
	v_sub_f32_e32 v79, v79, v184
	v_exp_f32_e32 v72, v72
	v_exp_f32_e32 v73, v73
	v_exp_f32_e32 v74, v74
	v_exp_f32_e32 v75, v75
	v_exp_f32_e32 v76, v76
	v_exp_f32_e32 v77, v77
	v_exp_f32_e32 v78, v78
	v_exp_f32_e32 v79, v79
	v_cvt_pk_bf16_f32 v188, v88, v89
	v_cvt_pk_bf16_f32 v189, v90, v91
	v_cvt_pk_bf16_f32 v190, v92, v93
	v_cvt_pk_bf16_f32 v191, v94, v66
	s_andn2_b64 vcc, exec, s[10:11]
	s_waitcnt lgkmcnt(1)
	v_mfma_f32_32x32x16_bf16 v[48:63], v[196:199], v[188:191], v[48:63]
	s_waitcnt lgkmcnt(0)
	v_mfma_f32_32x32x16_bf16 v[32:47], v[192:195], v[188:191], v[32:47]
	v_cvt_pk_bf16_f32 v188, v72, v73
	v_cvt_pk_bf16_f32 v189, v74, v75
	v_cvt_pk_bf16_f32 v190, v76, v77
	v_cvt_pk_bf16_f32 v191, v78, v79
	s_nop 1
	s_nop 1
	v_mfma_f32_32x32x16_bf16 v[16:31], v[196:199], v[188:191], v[16:31]
	v_mfma_f32_32x32x16_bf16 v[0:15], v[192:195], v[188:191], v[0:15]
	s_cmp_lg_u32 s101, 0
	s_cbranch_scc1 .LBB0_417
	s_cbranch_vccnz .LBB0_417
	s_waitcnt vmcnt(0)
	s_add_u32 s10, s100, 0x8a00
	s_cmp_eq_u32 s10, 0x19e00
	s_cselect_b32 s10, 0, s10
	v_add3_u32 v95, s10, v175, v166
	v_add3_u32 v182, s10, v176, v166
	v_add_u32_e32 v183, 0x4800, v182
	ds_write_b128 v95, v[130:133]
	ds_write_b128 v95, v[134:137] offset:9216
	ds_write2_b64 v183, v[154:155], v[156:157] offset1:1
	v_add_u32_e32 v95, 0x4880, v182
	ds_write2_b64 v95, v[158:159], v[160:161] offset1:1
	s_branch .LBB0_417
; #define LAS __attribute__((address_space(3)))
; __device__ __forceinline__ float shx(float v, int o, int lane) { return __builtin_bit_cast(float, __builtin_amdgcn_ds_bpermute((lane ^ o) << 2, __builtin_bit_cast(int, v))); }
; template <int DK, bool IS_A>
; __device__ __forceinline__ void attn_unit(const Params& P, int l, LAS unsigned char* lds, int b, int grp, int qtok0, int nkeys) {
;     ...
;     la += shx(la, 32, lane); lb_ += shx(lb_, 32, lane);
;     { const float ia = 1.0f / la, ib = 1.0f / lb_;
; #pragma unroll
;       for (int r = 0; r < 16; ++r) { oa0[r] *= ia; oa1[r] *= ia; ob0[r] *= ib; ob1[r] *= ib; } }
;     ...
;     if (IS_A) {
;         LAS float* X = (LAS float*)lds;
;         if (s == 1) {
; #pragma unroll
;             for (int r = 0; r < 16; ++r) { X[(wq * 64 + r) * 64 + lane] = oa0[r]; X[(wq * 64 + 16 + r) * 64 + lane] = oa1[r]; X[(wq * 64 + 32 + r) * 64 + lane] = ob0[r]; X[(wq * 64 + 48 + r) * 64 + lane] = ob1[r]; }
;         }
;         __syncthreads();
.LBB0_434:
	v_mov_b32_e32 v242, 0x400
	ds_bpermute_b32 v64, v163, v185
	ds_bpermute_b32 v65, v163, v180
	s_waitcnt lgkmcnt(1)
	v_add_f32_e32 v64, v185, v64
	v_div_scale_f32 v66, s[10:11], v64, v64, 1.0
	v_rcp_f32_e32 v67, v66
	s_waitcnt lgkmcnt(0)
	v_add_f32_e32 v65, v180, v65
	v_fma_f32 v68, -v66, v67, 1.0
	v_fmac_f32_e32 v67, v68, v67
	v_div_scale_f32 v68, vcc, 1.0, v64, 1.0
	v_mul_f32_e32 v69, v68, v67
	v_fma_f32 v70, -v66, v69, v68
	v_fmac_f32_e32 v69, v70, v67
	v_fma_f32 v66, -v66, v69, v68
	v_div_fmas_f32 v66, v66, v67, v69
	v_div_fixup_f32 v72, v66, v64, 1.0
	v_div_scale_f32 v64, s[10:11], v65, v65, 1.0
	v_rcp_f32_e32 v66, v64
	v_pk_mul_f32 v[36:37], v[36:37], v[72:73] op_sel_hi:[1,0]
	v_pk_mul_f32 v[70:71], v[54:55], v[72:73] op_sel_hi:[1,0]
	v_pk_mul_f32 v[56:57], v[56:57], v[72:73] op_sel_hi:[1,0]
	v_fma_f32 v67, -v64, v66, 1.0
	v_fmac_f32_e32 v66, v67, v66
	v_div_scale_f32 v67, vcc, 1.0, v65, 1.0
	v_mul_f32_e32 v68, v67, v66
	v_fma_f32 v69, -v64, v68, v67
	v_fmac_f32_e32 v68, v69, v66
	v_fma_f32 v64, -v64, v68, v67
	v_div_fmas_f32 v64, v64, v66, v68
	v_div_fixup_f32 v74, v64, v65, 1.0
	v_pk_mul_f32 v[66:67], v[50:51], v[72:73] op_sel_hi:[1,0]
	v_pk_mul_f32 v[50:51], v[34:35], v[72:73] op_sel_hi:[1,0]
	v_pk_mul_f32 v[34:35], v[18:19], v[74:75] op_sel_hi:[1,0]
	v_pk_mul_f32 v[18:19], v[2:3], v[74:75] op_sel_hi:[1,0]
	v_pk_mul_f32 v[2:3], v[6:7], v[74:75] op_sel_hi:[1,0]
	v_pk_mul_f32 v[6:7], v[24:25], v[74:75] op_sel_hi:[1,0]
	v_pk_mul_f32 v[24:25], v[28:29], v[74:75] op_sel_hi:[1,0]
	v_pk_mul_f32 v[28:29], v[14:15], v[74:75] op_sel_hi:[1,0]
	v_lshlrev_b32_e32 v14, 8, v173
	v_pk_mul_f32 v[64:65], v[48:49], v[72:73] op_sel_hi:[1,0]
	v_pk_mul_f32 v[48:49], v[32:33], v[72:73] op_sel_hi:[1,0]
	v_pk_mul_f32 v[32:33], v[16:17], v[74:75] op_sel_hi:[1,0]
	v_pk_mul_f32 v[16:17], v[0:1], v[74:75] op_sel_hi:[1,0]
	v_pk_mul_f32 v[68:69], v[52:53], v[72:73] op_sel_hi:[1,0]
	v_pk_mul_f32 v[20:21], v[20:21], v[74:75] op_sel_hi:[1,0]
	v_pk_mul_f32 v[0:1], v[4:5], v[74:75] op_sel_hi:[1,0]
	v_pk_mul_f32 v[52:53], v[38:39], v[72:73] op_sel_hi:[1,0]
	v_pk_mul_f32 v[22:23], v[22:23], v[74:75] op_sel_hi:[1,0]
	v_pk_mul_f32 v[54:55], v[40:41], v[72:73] op_sel_hi:[1,0]
	v_pk_mul_f32 v[4:5], v[8:9], v[74:75] op_sel_hi:[1,0]
	v_pk_mul_f32 v[38:39], v[58:59], v[72:73] op_sel_hi:[1,0]
	v_pk_mul_f32 v[40:41], v[42:43], v[72:73] op_sel_hi:[1,0]
	v_pk_mul_f32 v[8:9], v[26:27], v[74:75] op_sel_hi:[1,0]
	v_pk_mul_f32 v[10:11], v[10:11], v[74:75] op_sel_hi:[1,0]
	v_pk_mul_f32 v[42:43], v[60:61], v[72:73] op_sel_hi:[1,0]
	v_pk_mul_f32 v[44:45], v[44:45], v[72:73] op_sel_hi:[1,0]
	v_pk_mul_f32 v[12:13], v[12:13], v[74:75] op_sel_hi:[1,0]
	v_pk_mul_f32 v[58:59], v[62:63], v[72:73] op_sel_hi:[1,0]
	v_pk_mul_f32 v[46:47], v[46:47], v[72:73] op_sel_hi:[1,0]
	v_pk_mul_f32 v[26:27], v[30:31], v[74:75] op_sel_hi:[1,0]
	v_cmp_eq_u32_e32 vcc, 1, v172
	v_add3_u32 v60, 0, v174, v14
	s_and_saveexec_b64 s[10:11], vcc
	s_cbranch_execz .LBB0_436
	ds_write2st64_b32 v60, v64, v65 offset1:1
	ds_write2st64_b32 v60, v48, v49 offset0:16 offset1:17
	ds_write2st64_b32 v60, v32, v33 offset0:32 offset1:33
	ds_write2st64_b32 v60, v16, v17 offset0:48 offset1:49
	ds_write2st64_b32 v60, v66, v67 offset0:2 offset1:3
	ds_write2st64_b32 v60, v50, v51 offset0:18 offset1:19
	ds_write2st64_b32 v60, v34, v35 offset0:34 offset1:35
	ds_write2st64_b32 v60, v18, v19 offset0:50 offset1:51
	ds_write2st64_b32 v60, v68, v69 offset0:4 offset1:5
	ds_write2st64_b32 v60, v36, v37 offset0:20 offset1:21
	ds_write2st64_b32 v60, v20, v21 offset0:36 offset1:37
	ds_write2st64_b32 v60, v0, v1 offset0:52 offset1:53
	ds_write2st64_b32 v60, v70, v71 offset0:6 offset1:7
	ds_write2st64_b32 v60, v52, v53 offset0:22 offset1:23
	ds_write2st64_b32 v60, v22, v23 offset0:38 offset1:39
	ds_write2st64_b32 v60, v2, v3 offset0:54 offset1:55
	ds_write2st64_b32 v60, v56, v57 offset0:8 offset1:9
	ds_write2st64_b32 v60, v54, v55 offset0:24 offset1:25
	ds_write2st64_b32 v60, v6, v7 offset0:40 offset1:41
	ds_write2st64_b32 v60, v4, v5 offset0:56 offset1:57
	ds_write2st64_b32 v60, v38, v39 offset0:10 offset1:11
	ds_write2st64_b32 v60, v40, v41 offset0:26 offset1:27
	ds_write2st64_b32 v60, v8, v9 offset0:42 offset1:43
	ds_write2st64_b32 v60, v10, v11 offset0:58 offset1:59
	ds_write2st64_b32 v60, v42, v43 offset0:12 offset1:13
	ds_write2st64_b32 v60, v44, v45 offset0:28 offset1:29
	ds_write2st64_b32 v60, v24, v25 offset0:44 offset1:45
	ds_write2st64_b32 v60, v12, v13 offset0:60 offset1:61
	ds_write2st64_b32 v60, v58, v59 offset0:14 offset1:15
	ds_write2st64_b32 v60, v46, v47 offset0:30 offset1:31
	ds_write2st64_b32 v60, v26, v27 offset0:46 offset1:47
	ds_write2st64_b32 v60, v28, v29 offset0:62 offset1:63
